# static s_setprio 1 for waves 4-7 during the attention phase (reset to 0 before the next grid sync)
# baseline (speedup 1.0000x reference)
; #define LAS __attribute__((address_space(3)))
; __global__ void __launch_bounds__(512, 2) mega(Params P) {
;     ...
;                 LAS float* rpbL = (LAS float*)lds; int gw_o = (((int)blockIdx.x & 7) * 32 + ((int)blockIdx.x >> 3)) * 8 + wave; asm volatile("" : "+s"(gw_o));
;                 int tid_o = threadIdx.x; asm volatile("" : "+v"(tid_o)); const int lane_o = tid_o & 63;
;                 const float* rp = P.in[5] + (size_t)ly * 6 * 465;
;                 for (int i = tid_o; i < 6 * 465; i += 512) rpbL[i] = rp[i];
.LBB0_333:
	s_or_b64 exec, exec, s[34:35]
	v_readlane_b32 s4, v254, 16
	v_readlane_b32 s10, v254, 22
	v_readlane_b32 s18, v254, 30
	v_readlane_b32 s19, v254, 31
	s_mov_b64 s[42:43], s[18:19]
	v_readlane_b32 s10, v253, 22
	s_mov_b32 s81, s44
	v_readlane_b32 s1, v254, 42
	v_mov_b32_e32 v168, v238
	s_movk_i32 s2, 0xae6
	s_waitcnt lgkmcnt(0)
	s_barrier
	v_readfirstlane_b32 s20, v238
	s_nop 3
	s_lshr_b32 s20, s20, 6
	s_cmp_ge_u32 s20, 4
	s_cbranch_scc0 .Lprio_skip
	s_setprio 1
.Lprio_skip:
	v_readlane_b32 s5, v254, 17
	v_cmp_gt_i32_e32 vcc, s2, v168
	v_readlane_b32 s6, v254, 18
	v_readlane_b32 s7, v254, 19
	v_readlane_b32 s8, v254, 20
	v_readlane_b32 s9, v254, 21
	v_readlane_b32 s11, v254, 23
	v_readlane_b32 s12, v254, 24
	v_readlane_b32 s13, v254, 25
	v_readlane_b32 s14, v254, 26
	v_readlane_b32 s15, v254, 27
	v_readlane_b32 s16, v254, 28
	v_readlane_b32 s17, v254, 29
	s_and_saveexec_b64 s[2:3], vcc
	s_cbranch_execz .LBB0_341
	v_max_i32_e32 v0, 0x8e6, v168
	v_sub_u32_e32 v0, v0, v168
	v_add_u32_e32 v0, 0x1ff, v0
	s_movk_i32 s4, 0x1ff
	s_mul_hi_i32 s11, s81, 0x2b98
	s_mul_i32 s12, s81, 0x2b98
	v_cmp_lt_u32_e32 vcc, s4, v0
	s_mov_b64 s[6:7], -1
	v_mov_b32_e32 v2, v168
	s_and_saveexec_b64 s[4:5], vcc
	s_cbranch_execz .LBB0_338
	v_lshrrev_b32_e32 v0, 9, v0
	v_readlane_b32 s16, v254, 0
	v_add_u32_e32 v0, 1, v0
	v_readlane_b32 s26, v254, 10
	v_readlane_b32 s27, v254, 11
	s_add_u32 s6, s26, s12
	v_and_b32_e32 v4, 0xfffffe, v0
	v_add_u32_e32 v169, 0x200, v168
	s_addc_u32 s7, s27, s11
	v_lshl_add_u32 v5, v168, 2, 0
	s_mov_b64 s[8:9], 0
	v_mov_b32_e32 v6, v4
	v_mov_b64_e32 v[2:3], v[168:169]
	v_readlane_b32 s17, v254, 1
	v_readlane_b32 s18, v254, 2
	v_readlane_b32 s19, v254, 3
	v_readlane_b32 s20, v254, 4
	v_readlane_b32 s21, v254, 5
	v_readlane_b32 s22, v254, 6
	v_readlane_b32 s23, v254, 7
	v_readlane_b32 s24, v254, 8
	v_readlane_b32 s25, v254, 9
	v_readlane_b32 s28, v254, 12
	v_readlane_b32 s29, v254, 13
	v_readlane_b32 s30, v254, 14
	v_readlane_b32 s31, v254, 15

; __device__ __forceinline__ unsigned xb_add(unsigned* p, unsigned v) { return __hip_atomic_fetch_add(p, v, __ATOMIC_RELAXED, __HIP_MEMORY_SCOPE_AGENT); }
; __device__ __forceinline__ void xcd_barrier(const XcdBarrier& b) {
;     asm volatile("s_waitcnt vmcnt(0)" ::: "memory");
;     __syncthreads();
;     if (threadIdx.x == 0) {
;         unsigned* bar = b.bar;
;         __builtin_amdgcn_s_waitcnt(0);
;         unsigned nloc = b.st[0], nx = b.st[1];
;         if (nloc == 0u) { xcd_barrier_complete(bar, b.x, nloc, nx); b.st[0] = nloc; b.st[1] = nx; }
;         const unsigned old = xb_add(&bar[XB_XSUB(b.x)], 1u);
.LBB0_684:
	v_readlane_b32 s4, v254, 16
	v_readlane_b32 s18, v254, 30
	v_readlane_b32 s19, v254, 31
	s_mov_b64 s[42:43], s[18:19]
	s_barrier
	s_setprio 0
	s_getreg_b32 s1, hwreg(HW_REG_XCC_ID, 0, 4)
	s_waitcnt vmcnt(0)
	v_readlane_b32 s5, v254, 17
	v_readlane_b32 s6, v254, 18
	v_readlane_b32 s7, v254, 19
	v_readlane_b32 s8, v254, 20
	v_readlane_b32 s9, v254, 21
	v_readlane_b32 s10, v254, 22
	v_readlane_b32 s11, v254, 23
	v_readlane_b32 s12, v254, 24
	v_readlane_b32 s13, v254, 25
	v_readlane_b32 s14, v254, 26
	v_readlane_b32 s15, v254, 27
	v_readlane_b32 s16, v254, 28
	v_readlane_b32 s17, v254, 29
	s_barrier
	s_mov_b64 s[2:3], exec
	v_readlane_b32 s4, v254, 32
	v_readlane_b32 s5, v254, 33
	s_and_b64 s[4:5], s[2:3], s[4:5]
	s_xor_b64 s[34:35], s[4:5], s[2:3]
	s_mov_b64 exec, s[4:5]
	s_cbranch_execz .LBB0_729
	s_waitcnt vmcnt(0) lgkmcnt(0)
	v_mov_b32_e32 v0, 0x20008
	ds_read_b32 v2, v0
	s_waitcnt lgkmcnt(0)
	v_readfirstlane_b32 s4, v2
	s_nop 3
	s_cmp_lg_u32 s4, 0
	s_cbranch_scc1 .Lxk_known_P2
	v_readlane_b32 s10, v254, 30
	v_readlane_b32 s11, v254, 31
	s_nop 3
	s_add_u32 s10, s10, 0x300000
	s_addc_u32 s11, s11, 0
	v_mov_b32_e32 v3, 0
	s_nop 3
	global_load_dword v6, v3, s[10:11] offset:64 sc1
	global_load_dword v7, v3, s[10:11] offset:320 sc1
	global_load_dword v8, v3, s[10:11] offset:576 sc1
	global_load_dword v9, v3, s[10:11] offset:832 sc1
	global_load_dword v10, v3, s[10:11] offset:1088 sc1
	global_load_dword v11, v3, s[10:11] offset:1344 sc1
	global_load_dword v12, v3, s[10:11] offset:1600 sc1
	global_load_dword v13, v3, s[10:11] offset:1856 sc1
	s_waitcnt vmcnt(0)
	v_add_u32_e32 v14, -1, v6
	v_and_b32_e32 v14, v14, v6
	v_add_u32_e32 v15, -1, v7
	v_and_or_b32 v14, v15, v7, v14
	v_add_u32_e32 v15, -1, v8
	v_and_or_b32 v14, v15, v8, v14
	v_add_u32_e32 v15, -1, v9
	v_and_or_b32 v14, v15, v9, v14
	v_add_u32_e32 v15, -1, v10
	v_and_or_b32 v14, v15, v10, v14
	v_add_u32_e32 v15, -1, v11
	v_and_or_b32 v14, v15, v11, v14
	v_add_u32_e32 v15, -1, v12
	v_and_or_b32 v14, v15, v12, v14
	v_add_u32_e32 v15, -1, v13
	v_and_or_b32 v14, v15, v13, v14
	v_add3_u32 v16, v6, v7, v8
	v_add3_u32 v16, v16, v9, v10
	v_add3_u32 v16, v16, v11, v12
	v_add_u32_e32 v16, v16, v13
	v_xor_b32_e32 v16, 0xff, v16
	v_or_b32_e32 v14, v14, v16
	global_load_dword v6, v3, s[10:11] offset:1024 sc1
	global_load_dword v7, v3, s[10:11] offset:1280 sc1
	global_load_dword v8, v3, s[10:11] offset:1536 sc1
	global_load_dword v9, v3, s[10:11] offset:1792 sc1
	global_load_dword v10, v3, s[10:11] offset:2048 sc1
	global_load_dword v11, v3, s[10:11] offset:2304 sc1
	global_load_dword v12, v3, s[10:11] offset:2560 sc1
	global_load_dword v13, v3, s[10:11] offset:2816 sc1
	s_waitcnt vmcnt(0)
	v_xor_b32_e32 v6, 32, v6
	v_xor_b32_e32 v7, 32, v7
	v_xor_b32_e32 v8, 32, v8
	v_xor_b32_e32 v9, 32, v9
	v_xor_b32_e32 v10, 32, v10
	v_xor_b32_e32 v11, 32, v11
	v_xor_b32_e32 v12, 32, v12
	v_xor_b32_e32 v13, 32, v13
	v_or3_b32 v14, v14, v6, v7
	v_or3_b32 v14, v14, v8, v9
	v_or3_b32 v14, v14, v10, v11
	v_or3_b32 v14, v14, v12, v13
	s_nop 1
	v_readfirstlane_b32 s4, v14
	s_nop 3
	s_cmp_eq_u32 s4, 0
	s_cselect_b32 s4, 1, 2
	v_mov_b32_e32 v2, s4
	ds_write_b32 v0, v2
	s_waitcnt lgkmcnt(0)
